# speedup vs baseline: 1.0057x; 1.0026x over previous
; #define SCHED() __builtin_amdgcn_sched_barrier(0)
; #define DSR(dst, addr, off) asm volatile("ds_read_b128 %0, %1 offset:%2" : "=&v"(dst) : "v"(addr), "n"(off) : "memory")
; #define LGKM(n) asm volatile("s_waitcnt lgkmcnt(%0)" ::"n"(n) : "memory")
; #define DSR(dst, addr, off) asm volatile("ds_read_b128 %0, %1 offset:%2" : "=&v"(dst) : "v"(addr), "n"(off) : "memory")
; #define LGKM(n) asm volatile("s_waitcnt lgkmcnt(%0)" ::"n"(n) : "memory")
; __device__ __forceinline__ void attn_phase(char* shm, const Params& p, const u16* __restrict__ qb, const u16* __restrict__ kb,
;                                            const u16* __restrict__ vT, u16* __restrict__ attn) {
;     ...
;         const float df = (float)(kt * 64 + u * 32 + 4 * hh - qpos);
;         bf16x8 P[2][2];
;         bf16x8 kf[2], qf[2];
;         DSR(kf[0], kb_ + kL0, u * 8192); DSR(qf[0], qaddr, 0);
; #pragma unroll
;         for (int c = 0; c < 2; ++c) {
;           f32x16 Sx;
; #pragma unroll
;           for (int i = 0; i < 16; ++i) Sx[i] = -sl2 * fabsf(df + (float)((i & 3) + 8 * (i >> 2)));
; #pragma unroll
;           for (int ks = 0; ks < 4; ++ks) {
;             const int f = c * 4 + ks;
;             if (f < 7) {
;               DSR(kf[(f + 1) & 1], kb_ + (kL0 ^ ((((f + 1) >> 2) * 8 + ((f + 1) & 3) * 2) << 4)), u * 8192);
;               DSR(qf[(f + 1) & 1], qaddr, (f + 1) * 1024);
;               LGKM(2);
;             } else LGKM(0);
;             SCHED();
;             Sx = __builtin_amdgcn_mfma_f32_32x32x16_bf16(kf[f & 1], qf[f & 1], Sx, 0, 0, 0);
;             SCHED();
;           }
;           float pv[16];
; #pragma unroll
;           for (int i = 0; i < 16; ++i) { pv[i] = __builtin_amdgcn_exp2f(Sx[i]); lsum[c] += pv[i]; }
; #pragma unroll
;           for (int a = 0; a < 2; ++a) {
;             i32x4 t4;
; #pragma unroll
;             for (int i = 0; i < 4; ++i) t4[i] = pk_bf16(pv[a * 8 + 2 * i], pv[a * 8 + 2 * i + 1]);
;             P[c][a] = __builtin_bit_cast(bf16x8, t4);
;           }
;         }
;         bf16x8 vf[2];
;         DSR(vf[0], vb_ + (vM0 ^ ((u * 4) << 4)), 0);
.LBB0_299:
	v_cvt_f32_i32_e32 v128, v205
	v_add_u32_e32 v160, s44, v188
	ds_read_b128 v[206:209], v160 offset:0
	ds_read_b128 v[210:213], v185 offset:0
	v_add_u32_e32 v214, s44, v190
	ds_read_b128 v[218:221], v214 offset:0
	ds_read_b128 v[222:225], v185 offset:0x400
	v_add_f32_e32 v129, 1.0, v128
	s_waitcnt lgkmcnt(2)
	v_pk_add_f32 v[130:131], v[128:129], s[12:13] op_sel_hi:[0,1]
	v_pk_add_f32 v[132:133], v[128:129], s[14:15] op_sel_hi:[0,1]
	v_pk_add_f32 v[134:135], v[128:129], s[20:21] op_sel_hi:[0,1]
	v_pk_add_f32 v[136:137], v[128:129], s[22:23] op_sel_hi:[0,1]
	v_pk_add_f32 v[138:139], v[128:129], s[24:25] op_sel_hi:[0,1]
	v_pk_add_f32 v[140:141], v[128:129], s[26:27] op_sel_hi:[0,1]
	v_pk_add_f32 v[142:143], v[128:129], s[28:29] op_sel_hi:[0,1]
	v_and_b32_e32 v131, 0x7fffffff, v131
	v_and_b32_e32 v130, 0x7fffffff, v130
	v_and_b32_e32 v133, 0x7fffffff, v133
	v_and_b32_e32 v132, 0x7fffffff, v132
	v_and_b32_e32 v135, 0x7fffffff, v135
	v_and_b32_e32 v134, 0x7fffffff, v134
	v_and_b32_e32 v137, 0x7fffffff, v137
	v_and_b32_e32 v136, 0x7fffffff, v136
	v_and_b32_e32 v139, 0x7fffffff, v139
	v_and_b32_e32 v138, 0x7fffffff, v138
	v_and_b32_e32 v141, 0x7fffffff, v141
	v_and_b32_e32 v140, 0x7fffffff, v140
	v_and_b32_e32 v143, 0x7fffffff, v143
	v_and_b32_e32 v142, 0x7fffffff, v142
	v_and_b32_e32 v128, 0x7fffffff, v128
	v_and_b32_e32 v129, 0x7fffffff, v129
	s_add_i32 s0, s44, 0x4000
	v_pk_mul_f32 v[142:143], v[178:179], v[142:143]
	v_pk_mul_f32 v[140:141], v[178:179], v[140:141]
	v_pk_mul_f32 v[138:139], v[178:179], v[138:139]
	v_pk_mul_f32 v[136:137], v[178:179], v[136:137]
	v_pk_mul_f32 v[134:135], v[178:179], v[134:135]
	v_pk_mul_f32 v[132:133], v[178:179], v[132:133]
	v_pk_mul_f32 v[130:131], v[178:179], v[130:131]
	v_pk_mul_f32 v[128:129], v[170:171], v[128:129]
	s_nop 1
	v_mfma_f32_32x32x16_bf16 v[144:159], v[206:209], v[210:213], v[128:143]
	v_add_u32_e32 v215, s44, v191
	ds_read_b128 v[206:209], v215 offset:0
	ds_read_b128 v[210:213], v185 offset:0x800
	s_waitcnt lgkmcnt(2)
	v_mfma_f32_32x32x16_bf16 v[144:159], v[218:221], v[222:225], v[144:159]
	v_add_u32_e32 v226, s44, v192
	ds_read_b128 v[218:221], v226 offset:0
	ds_read_b128 v[222:225], v185 offset:0xc00
	s_waitcnt lgkmcnt(2)
	v_mfma_f32_32x32x16_bf16 v[144:159], v[206:209], v[210:213], v[144:159]
	v_add_u32_e32 v227, s44, v193
	ds_read_b128 v[206:209], v227 offset:0
	ds_read_b128 v[210:213], v185 offset:0x1000
	s_waitcnt lgkmcnt(2)
	v_mfma_f32_32x32x16_bf16 v[144:159], v[218:221], v[222:225], v[144:159]
	s_nop 11
	v_exp_f32_e32 v144, v144
	v_exp_f32_e32 v145, v145
	v_exp_f32_e32 v146, v146
	v_exp_f32_e32 v147, v147
	v_add_f32_e32 v181, v181, v144
	v_exp_f32_e32 v148, v148
	v_add_f32_e32 v181, v145, v181
	v_exp_f32_e32 v149, v149
	v_add_f32_e32 v181, v146, v181
	v_exp_f32_e32 v150, v150
	v_add_f32_e32 v181, v147, v181
	v_exp_f32_e32 v151, v151
	v_add_f32_e32 v181, v148, v181
	v_exp_f32_e32 v152, v152
	v_add_f32_e32 v181, v149, v181
	v_exp_f32_e32 v153, v153
	v_add_f32_e32 v181, v150, v181
	v_exp_f32_e32 v154, v154
	v_add_f32_e32 v181, v151, v181
	v_exp_f32_e32 v155, v155
	v_add_f32_e32 v181, v152, v181
	v_exp_f32_e32 v156, v156
	v_add_f32_e32 v181, v153, v181
	v_exp_f32_e32 v157, v157
	v_add_f32_e32 v181, v154, v181
	v_exp_f32_e32 v158, v158
	v_add_f32_e32 v181, v155, v181
	v_exp_f32_e32 v159, v159
	v_add_f32_e32 v181, v156, v181
	v_add_f32_e32 v181, v157, v181
	v_add_f32_e32 v181, v158, v181
	v_cvt_pk_bf16_f32 v144, v144, v145
	v_cvt_pk_bf16_f32 v145, v146, v147
	v_cvt_pk_bf16_f32 v146, v148, v149
	v_cvt_pk_bf16_f32 v148, v152, v153
	v_cvt_pk_bf16_f32 v149, v154, v155
	v_add_u32_e32 v229, s44, v194
	ds_read_b128 v[152:155], v229 offset:0
	v_add_f32_e32 v181, v159, v181
	v_cvt_pk_bf16_f32 v147, v150, v151
	v_cvt_pk_bf16_f32 v150, v156, v157
	v_cvt_pk_bf16_f32 v151, v158, v159
	ds_read_b128 v[156:159], v185 offset:0x1400
	s_waitcnt lgkmcnt(2)
	v_mfma_f32_32x32x16_bf16 v[128:143], v[206:209], v[210:213], v[128:143]
	v_add_u32_e32 v230, s44, v195
	ds_read_b128 v[206:209], v230 offset:0
	ds_read_b128 v[210:213], v185 offset:0x1800
	s_waitcnt lgkmcnt(2)
	v_mfma_f32_32x32x16_bf16 v[128:143], v[152:155], v[156:159], v[128:143]
	v_add_u32_e32 v232, s44, v196
	ds_read_b128 v[152:155], v232 offset:0
	ds_read_b128 v[156:159], v185 offset:0x1c00
	s_waitcnt lgkmcnt(2)
	v_mfma_f32_32x32x16_bf16 v[128:143], v[206:209], v[210:213], v[128:143]
	s_waitcnt lgkmcnt(0)
	v_mfma_f32_32x32x16_bf16 v[128:143], v[152:155], v[156:159], v[128:143]
	s_nop 11
	v_exp_f32_e32 v128, v128
	v_exp_f32_e32 v129, v129
	v_exp_f32_e32 v130, v130
	v_exp_f32_e32 v131, v131
	v_add_f32_e32 v152, v180, v128
	v_exp_f32_e32 v132, v132
	v_add_f32_e32 v152, v129, v152
	v_exp_f32_e32 v133, v133
	v_add_f32_e32 v152, v130, v152
	v_exp_f32_e32 v134, v134
	v_add_f32_e32 v152, v131, v152
	v_exp_f32_e32 v135, v135
	v_add_f32_e32 v152, v132, v152
	v_exp_f32_e32 v136, v136
	v_add_f32_e32 v152, v133, v152
	v_exp_f32_e32 v137, v137
	v_add_f32_e32 v152, v134, v152
	v_exp_f32_e32 v138, v138
	v_add_f32_e32 v152, v135, v152
	v_exp_f32_e32 v139, v139
	v_add_f32_e32 v152, v136, v152
	v_exp_f32_e32 v140, v140
	v_add_f32_e32 v152, v137, v152
	v_exp_f32_e32 v141, v141
	v_add_f32_e32 v152, v138, v152
	v_exp_f32_e32 v142, v142
	v_add_f32_e32 v152, v139, v152
	v_exp_f32_e32 v143, v143
	v_add_f32_e32 v152, v140, v152
	v_add_f32_e32 v152, v141, v152
	v_add_f32_e32 v152, v142, v152
	v_add_f32_e32 v180, v143, v152
	v_cvt_pk_bf16_f32 v128, v128, v129
	v_cvt_pk_bf16_f32 v129, v130, v131
	v_cvt_pk_bf16_f32 v130, v132, v133
	v_cvt_pk_bf16_f32 v132, v136, v137
	v_cvt_pk_bf16_f32 v133, v138, v139
	v_add_u32_e32 v152, s0, v189
	ds_read_b128 v[136:139], v152 offset:0
	v_cvt_pk_bf16_f32 v131, v134, v135
	v_cvt_pk_bf16_f32 v134, v140, v141
	v_cvt_pk_bf16_f32 v135, v142, v143
	ds_read_b128 v[140:143], v152 offset:0x1000
	s_waitcnt lgkmcnt(1)
	v_or3_b32 v240, v128, v129, v130
	v_or3_b32 v240, v240, v131, v132
	v_or3_b32 v240, v240, v133, v134
	v_or3_b32 v240, v240, v135, v144
	v_or3_b32 v240, v240, v145, v146
	v_or3_b32 v240, v240, v147, v148
	v_or3_b32 v240, v240, v149, v150
	v_or_b32_e32 v240, v240, v151
	v_cmp_ne_u32_e32 vcc, 0, v240
	s_and_b64 vcc, exec, vcc
	s_cbranch_vccz .Lattn_pv_zero_0
; #define SCHED() __builtin_amdgcn_sched_barrier(0)
; #define DSR(dst, addr, off) asm volatile("ds_read_b128 %0, %1 offset:%2" : "=&v"(dst) : "v"(addr), "n"(off) : "memory")
; #define LGKM(n) asm volatile("s_waitcnt lgkmcnt(%0)" ::"n"(n) : "memory")
; #define DSR(dst, addr, off) asm volatile("ds_read_b128 %0, %1 offset:%2" : "=&v"(dst) : "v"(addr), "n"(off) : "memory")
; #define LGKM(n) asm volatile("s_waitcnt lgkmcnt(%0)" ::"n"(n) : "memory")
; __device__ __forceinline__ void attn_phase(char* shm, const Params& p, const u16* __restrict__ qb, const u16* __restrict__ kb,
;                                            const u16* __restrict__ vT, u16* __restrict__ attn) {
;     ...
;         const float df = (float)(kt * 64 + u * 32 + 4 * hh - qpos);
;         bf16x8 P[2][2];
;         bf16x8 kf[2], qf[2];
;         DSR(kf[0], kb_ + kL0, u * 8192); DSR(qf[0], qaddr, 0);
; #pragma unroll
;         for (int c = 0; c < 2; ++c) {
;           f32x16 Sx;
; #pragma unroll
;           for (int i = 0; i < 16; ++i) Sx[i] = -sl2 * fabsf(df + (float)((i & 3) + 8 * (i >> 2)));
; #pragma unroll
;           for (int ks = 0; ks < 4; ++ks) {
;             const int f = c * 4 + ks;
;             if (f < 7) {
;               DSR(kf[(f + 1) & 1], kb_ + (kL0 ^ ((((f + 1) >> 2) * 8 + ((f + 1) & 3) * 2) << 4)), u * 8192);
;               DSR(qf[(f + 1) & 1], qaddr, (f + 1) * 1024);
;               LGKM(2);
;             } else LGKM(0);
;             SCHED();
;             Sx = __builtin_amdgcn_mfma_f32_32x32x16_bf16(kf[f & 1], qf[f & 1], Sx, 0, 0, 0);
;             SCHED();
;           }
;           float pv[16];
; #pragma unroll
;           for (int i = 0; i < 16; ++i) { pv[i] = __builtin_amdgcn_exp2f(Sx[i]); lsum[c] += pv[i]; }
;     ...
;         DSR(vf[0], vb_ + (vM0 ^ ((u * 4) << 4)), 0);
; #pragma unroll
;         for (int g = 0; g < 8; ++g) {
;           const int a = g >> 2, t = g & 3;
;           if (g < 7) { DSR(vf[(g + 1) & 1], vb_ + (vM0 ^ ((u * 4 + ((g + 1) >> 2) * 2) << 4)), ((g + 1) & 3) * 4096); LGKM(1); }
;           else LGKM(0);
;           SCHED();
;           O[0][t] = __builtin_amdgcn_mfma_f32_32x32x16_bf16(vf[g & 1], P[0][a], O[0][t], 0, 0, 0);
;           O[1][t] = __builtin_amdgcn_mfma_f32_32x32x16_bf16(vf[g & 1], P[1][a], O[1][t], 0, 0, 0);
;           SCHED();
;         }
	v_mfma_f32_32x32x16_bf16 v[112:127], v[136:139], v[144:147], v[112:127]
	v_mfma_f32_32x32x16_bf16 v[96:111], v[136:139], v[128:131], v[96:111]
	ds_read_b128 v[136:139], v152 offset:0x2000
	s_waitcnt lgkmcnt(1)
	v_mfma_f32_32x32x16_bf16 v[80:95], v[140:143], v[144:147], v[80:95]
	v_mfma_f32_32x32x16_bf16 v[64:79], v[140:143], v[128:131], v[64:79]
	ds_read_b128 v[140:143], v152 offset:0x3000
	s_waitcnt lgkmcnt(1)
	v_mfma_f32_32x32x16_bf16 v[48:63], v[136:139], v[144:147], v[48:63]
	v_mfma_f32_32x32x16_bf16 v[16:31], v[136:139], v[128:131], v[16:31]
	v_add_u32_e32 v152, s0, v197
	ds_read_b128 v[136:139], v152 offset:0
	s_waitcnt lgkmcnt(1)
	v_mfma_f32_32x32x16_bf16 v[32:47], v[140:143], v[144:147], v[32:47]
	v_mfma_f32_32x32x16_bf16 v[0:15], v[140:143], v[128:131], v[0:15]
	ds_read_b128 v[128:131], v152 offset:0x1000
	s_waitcnt lgkmcnt(1)
	v_mfma_f32_32x32x16_bf16 v[112:127], v[136:139], v[148:151], v[112:127]
	v_mfma_f32_32x32x16_bf16 v[96:111], v[136:139], v[132:135], v[96:111]
	ds_read_b128 v[136:139], v152 offset:0x2000
	s_waitcnt lgkmcnt(1)
	v_mfma_f32_32x32x16_bf16 v[80:95], v[128:131], v[148:151], v[80:95]
	v_mfma_f32_32x32x16_bf16 v[64:79], v[128:131], v[132:135], v[64:79]
	ds_read_b128 v[128:131], v152 offset:0x3000
	s_waitcnt lgkmcnt(1)
	v_mfma_f32_32x32x16_bf16 v[48:63], v[136:139], v[148:151], v[48:63]
	v_mfma_f32_32x32x16_bf16 v[16:31], v[136:139], v[132:135], v[16:31]
	s_waitcnt lgkmcnt(0)
	v_mfma_f32_32x32x16_bf16 v[32:47], v[128:131], v[148:151], v[32:47]
	v_mfma_f32_32x32x16_bf16 v[0:15], v[128:131], v[132:135], v[0:15]
.Lattn_pv_zero_0:
	s_waitcnt lgkmcnt(0)
	v_add_u32_e32 v128, 32, v205
	v_cvt_f32_i32_e32 v128, v128
	ds_read_b128 v[206:209], v160 offset:0x2000
	ds_read_b128 v[210:213], v185 offset:0
	ds_read_b128 v[218:221], v214 offset:0x2000
	ds_read_b128 v[222:225], v185 offset:0x400
	v_add_f32_e32 v129, 1.0, v128
	s_waitcnt lgkmcnt(2)
	v_add_f32_e64 v130, v128, s12
	v_add_f32_e64 v131, v128, s13
	v_pk_add_f32 v[132:133], v[128:129], s[14:15] op_sel_hi:[0,1]
	v_pk_add_f32 v[134:135], v[128:129], s[20:21] op_sel_hi:[0,1]
	v_pk_add_f32 v[136:137], v[128:129], s[22:23] op_sel_hi:[0,1]
	v_pk_add_f32 v[138:139], v[128:129], s[24:25] op_sel_hi:[0,1]
	v_pk_add_f32 v[140:141], v[128:129], s[26:27] op_sel_hi:[0,1]
	v_pk_add_f32 v[142:143], v[128:129], s[28:29] op_sel_hi:[0,1]
	v_and_b32_e32 v131, 0x7fffffff, v131
	v_and_b32_e32 v130, 0x7fffffff, v130
	v_and_b32_e32 v133, 0x7fffffff, v133
	v_and_b32_e32 v132, 0x7fffffff, v132
	v_and_b32_e32 v135, 0x7fffffff, v135
	v_and_b32_e32 v134, 0x7fffffff, v134
	v_and_b32_e32 v137, 0x7fffffff, v137
	v_and_b32_e32 v136, 0x7fffffff, v136
	v_and_b32_e32 v139, 0x7fffffff, v139
	v_and_b32_e32 v138, 0x7fffffff, v138
	v_and_b32_e32 v141, 0x7fffffff, v141
	v_and_b32_e32 v140, 0x7fffffff, v140
	v_and_b32_e32 v143, 0x7fffffff, v143
	v_and_b32_e32 v142, 0x7fffffff, v142
	v_and_b32_e32 v128, 0x7fffffff, v128
	v_and_b32_e32 v129, 0x7fffffff, v129
	v_pk_mul_f32 v[142:143], v[178:179], v[142:143]
	v_pk_mul_f32 v[140:141], v[178:179], v[140:141]
	v_pk_mul_f32 v[138:139], v[178:179], v[138:139]
	v_pk_mul_f32 v[136:137], v[178:179], v[136:137]
	v_pk_mul_f32 v[134:135], v[178:179], v[134:135]
	v_pk_mul_f32 v[132:133], v[178:179], v[132:133]
	v_pk_mul_f32 v[130:131], v[178:179], v[130:131]
	v_pk_mul_f32 v[128:129], v[170:171], v[128:129]
	s_nop 1
	v_mfma_f32_32x32x16_bf16 v[144:159], v[206:209], v[210:213], v[128:143]
	ds_read_b128 v[206:209], v215 offset:0x2000
	ds_read_b128 v[210:213], v185 offset:0x800
	s_waitcnt lgkmcnt(2)
	v_mfma_f32_32x32x16_bf16 v[144:159], v[218:221], v[222:225], v[144:159]
	ds_read_b128 v[218:221], v226 offset:0x2000
	ds_read_b128 v[222:225], v185 offset:0xc00
	s_waitcnt lgkmcnt(2)
	v_mfma_f32_32x32x16_bf16 v[144:159], v[206:209], v[210:213], v[144:159]
	ds_read_b128 v[206:209], v227 offset:0x2000
	ds_read_b128 v[210:213], v185 offset:0x1000
	s_waitcnt lgkmcnt(2)
	v_mfma_f32_32x32x16_bf16 v[144:159], v[218:221], v[222:225], v[144:159]
	s_nop 11
	v_exp_f32_e32 v144, v144
	v_exp_f32_e32 v145, v145
	v_exp_f32_e32 v146, v146
	v_exp_f32_e32 v147, v147
	v_add_f32_e32 v160, v181, v144
	v_exp_f32_e32 v148, v148
	v_exp_f32_e32 v215, v149
	v_add_f32_e32 v160, v145, v160
	v_add_f32_e32 v160, v146, v160
	v_add_f32_e32 v160, v147, v160
	v_add_f32_e32 v181, v148, v160
	v_exp_f32_e32 v219, v150
	v_exp_f32_e32 v221, v151
	v_cvt_pk_bf16_f32 v144, v144, v145
	v_cvt_pk_bf16_f32 v145, v146, v147
	v_cvt_pk_bf16_f32 v146, v148, v215
	ds_read_b128 v[148:151], v229 offset:0x2000
	v_exp_f32_e32 v223, v152
	v_exp_f32_e32 v225, v153
	v_exp_f32_e32 v227, v154
	v_exp_f32_e32 v231, v155
	ds_read_b128 v[152:155], v185 offset:0x1400
	s_waitcnt lgkmcnt(2)
; #define WAIT_V(n) asm volatile("s_waitcnt vmcnt(%0)" ::"n"(n) : "memory")
; #define SCHED() __builtin_amdgcn_sched_barrier(0)
; #define DSR(dst, addr, off) asm volatile("ds_read_b128 %0, %1 offset:%2" : "=&v"(dst) : "v"(addr), "n"(off) : "memory")
; #define LGKM(n) asm volatile("s_waitcnt lgkmcnt(%0)" ::"n"(n) : "memory")
; #define DSR(dst, addr, off) asm volatile("ds_read_b128 %0, %1 offset:%2" : "=&v"(dst) : "v"(addr), "n"(off) : "memory")
; __device__ __forceinline__ void attn_phase(char* shm, const Params& p, const u16* __restrict__ qb, const u16* __restrict__ kb,
;                                            const u16* __restrict__ vT, u16* __restrict__ attn) {
;     ...
;           for (int i = 0; i < 16; ++i) Sx[i] = -sl2 * fabsf(df + (float)((i & 3) + 8 * (i >> 2)));
; #pragma unroll
;           for (int ks = 0; ks < 4; ++ks) {
;             const int f = c * 4 + ks;
;             if (f < 7) {
;               DSR(kf[(f + 1) & 1], kb_ + (kL0 ^ ((((f + 1) >> 2) * 8 + ((f + 1) & 3) * 2) << 4)), u * 8192);
;               DSR(qf[(f + 1) & 1], qaddr, (f + 1) * 1024);
;               LGKM(2);
;             } else LGKM(0);
;             SCHED();
;             Sx = __builtin_amdgcn_mfma_f32_32x32x16_bf16(kf[f & 1], qf[f & 1], Sx, 0, 0, 0);
;             SCHED();
;           }
;           float pv[16];
; #pragma unroll
;           for (int i = 0; i < 16; ++i) { pv[i] = __builtin_amdgcn_exp2f(Sx[i]); lsum[c] += pv[i]; }
; #pragma unroll
;           for (int a = 0; a < 2; ++a) {
;             i32x4 t4;
; #pragma unroll
;             for (int i = 0; i < 4; ++i) t4[i] = pk_bf16(pv[a * 8 + 2 * i], pv[a * 8 + 2 * i + 1]);
;             P[c][a] = __builtin_bit_cast(bf16x8, t4);
;           }
;         }
;         bf16x8 vf[2];
;         DSR(vf[0], vb_ + (vM0 ^ ((u * 4) << 4)), 0);
; #pragma unroll
;         for (int g = 0; g < 8; ++g) {
;           const int a = g >> 2, t = g & 3;
;           if (g < 7) { DSR(vf[(g + 1) & 1], vb_ + (vM0 ^ ((u * 4 + ((g + 1) >> 2) * 2) << 4)), ((g + 1) & 3) * 4096); LGKM(1); }
;           else LGKM(0);
;           SCHED();
;           O[0][t] = __builtin_amdgcn_mfma_f32_32x32x16_bf16(vf[g & 1], P[0][a], O[0][t], 0, 0, 0);
;           O[1][t] = __builtin_amdgcn_mfma_f32_32x32x16_bf16(vf[g & 1], P[1][a], O[1][t], 0, 0, 0);
;           SCHED();
;         }
;       }
;     ...
;       WAIT_V(0); __syncthreads();
	v_exp_f32_e32 v233, v156
	v_exp_f32_e32 v235, v157
	v_exp_f32_e32 v237, v158
	v_exp_f32_e32 v239, v159
	v_mfma_f32_32x32x16_bf16 v[128:143], v[206:209], v[210:213], v[128:143]
	ds_read_b128 v[156:159], v230 offset:0x2000
	ds_read_b128 v[206:209], v185 offset:0x1800
	s_waitcnt lgkmcnt(2)
	v_mfma_f32_32x32x16_bf16 v[128:143], v[148:151], v[152:155], v[128:143]
	ds_read_b128 v[148:151], v232 offset:0x2000
	ds_read_b128 v[152:155], v185 offset:0x1c00
	s_waitcnt lgkmcnt(2)
	v_mfma_f32_32x32x16_bf16 v[128:143], v[156:159], v[206:209], v[128:143]
	s_waitcnt lgkmcnt(0)
	v_mfma_f32_32x32x16_bf16 v[128:143], v[148:151], v[152:155], v[128:143]
	s_nop 11
	v_exp_f32_e32 v148, v128
	v_exp_f32_e32 v149, v129
	v_exp_f32_e32 v150, v130
	v_exp_f32_e32 v151, v131
	v_add_f32_e32 v128, v180, v148
	v_exp_f32_e32 v152, v132
	v_add_f32_e32 v128, v149, v128
	v_exp_f32_e32 v214, v133
	v_add_f32_e32 v128, v150, v128
	v_exp_f32_e32 v218, v134
	v_add_f32_e32 v128, v151, v128
	v_exp_f32_e32 v220, v135
	v_add_f32_e32 v180, v152, v128
	v_exp_f32_e32 v222, v136
	v_exp_f32_e32 v224, v137
	v_pk_add_f32 v[128:129], v[214:215], v[180:181]
	v_exp_f32_e32 v226, v138
	v_pk_add_f32 v[128:129], v[218:219], v[128:129]
	v_exp_f32_e32 v230, v139
	v_pk_add_f32 v[128:129], v[220:221], v[128:129]
	v_exp_f32_e32 v232, v140
	v_pk_add_f32 v[128:129], v[222:223], v[128:129]
	v_exp_f32_e32 v234, v141
	v_pk_add_f32 v[128:129], v[224:225], v[128:129]
	v_exp_f32_e32 v236, v142
	v_pk_add_f32 v[128:129], v[226:227], v[128:129]
	v_exp_f32_e32 v238, v143
	v_pk_add_f32 v[128:129], v[230:231], v[128:129]
	v_cvt_pk_bf16_f32 v134, v152, v214
	v_pk_add_f32 v[128:129], v[232:233], v[128:129]
	v_add_u32_e32 v152, s0, v198
	v_pk_add_f32 v[128:129], v[234:235], v[128:129]
	ds_read_b128 v[140:143], v152 offset:0
	v_cvt_pk_bf16_f32 v147, v219, v221
	v_pk_add_f32 v[132:133], v[236:237], v[128:129]
	v_cvt_pk_bf16_f32 v128, v223, v225
	v_pk_add_f32 v[180:181], v[238:239], v[132:133]
	v_cvt_pk_bf16_f32 v132, v148, v149
	v_cvt_pk_bf16_f32 v133, v150, v151
	ds_read_b128 v[148:151], v152 offset:0x1000
	s_waitcnt lgkmcnt(1)
	v_cvt_pk_bf16_f32 v129, v227, v231
	v_cvt_pk_bf16_f32 v130, v233, v235
	v_cvt_pk_bf16_f32 v131, v237, v239
	v_cvt_pk_bf16_f32 v135, v218, v220
	v_cvt_pk_bf16_f32 v136, v222, v224
	v_cvt_pk_bf16_f32 v137, v226, v230
	v_cvt_pk_bf16_f32 v138, v232, v234
	v_cvt_pk_bf16_f32 v139, v236, v238
	v_or3_b32 v240, v128, v129, v130
	v_or3_b32 v240, v240, v131, v132
	v_or3_b32 v240, v240, v133, v134
	v_or3_b32 v240, v240, v135, v136
	v_or3_b32 v240, v240, v137, v138
	v_or3_b32 v240, v240, v139, v144
	v_or3_b32 v240, v240, v145, v146
	v_or_b32_e32 v240, v240, v147
	v_cmp_ne_u32_e32 vcc, 0, v240
	s_and_b64 vcc, exec, vcc
	s_cbranch_vccz .Lattn_pv_zero_1
	v_mfma_f32_32x32x16_bf16 v[112:127], v[140:143], v[144:147], v[112:127]
	v_mfma_f32_32x32x16_bf16 v[96:111], v[140:143], v[132:135], v[96:111]
	ds_read_b128 v[140:143], v152 offset:0x2000
	s_waitcnt lgkmcnt(1)
	v_mfma_f32_32x32x16_bf16 v[80:95], v[148:151], v[144:147], v[80:95]
	v_mfma_f32_32x32x16_bf16 v[64:79], v[148:151], v[132:135], v[64:79]
	ds_read_b128 v[148:151], v152 offset:0x3000
	s_waitcnt lgkmcnt(1)
	v_mfma_f32_32x32x16_bf16 v[48:63], v[140:143], v[144:147], v[48:63]
	v_mfma_f32_32x32x16_bf16 v[16:31], v[140:143], v[132:135], v[16:31]
	v_add_u32_e32 v152, s0, v199
	ds_read_b128 v[140:143], v152 offset:0
	s_waitcnt lgkmcnt(1)
	v_mfma_f32_32x32x16_bf16 v[32:47], v[148:151], v[144:147], v[32:47]
	v_mfma_f32_32x32x16_bf16 v[0:15], v[148:151], v[132:135], v[0:15]
	ds_read_b128 v[132:135], v152 offset:0x1000
	s_waitcnt lgkmcnt(1)
	v_mfma_f32_32x32x16_bf16 v[112:127], v[140:143], v[128:131], v[112:127]
	v_mfma_f32_32x32x16_bf16 v[96:111], v[140:143], v[136:139], v[96:111]
	ds_read_b128 v[140:143], v152 offset:0x2000
	s_waitcnt lgkmcnt(1)
	v_mfma_f32_32x32x16_bf16 v[80:95], v[132:135], v[128:131], v[80:95]
	v_mfma_f32_32x32x16_bf16 v[64:79], v[132:135], v[136:139], v[64:79]
	ds_read_b128 v[132:135], v152 offset:0x3000
	s_waitcnt lgkmcnt(1)
	v_mfma_f32_32x32x16_bf16 v[48:63], v[140:143], v[128:131], v[48:63]
	v_mfma_f32_32x32x16_bf16 v[16:31], v[140:143], v[136:139], v[16:31]
	s_waitcnt lgkmcnt(0)
	v_mfma_f32_32x32x16_bf16 v[32:47], v[132:135], v[128:131], v[32:47]
	v_mfma_f32_32x32x16_bf16 v[0:15], v[132:135], v[136:139], v[0:15]
.Lattn_pv_zero_1:
	s_waitcnt lgkmcnt(0)
	s_waitcnt vmcnt(0)
	v_add_u32_e32 v205, 64, v205
	v_lshl_add_u64 v[172:173], v[172:173], 0, s[30:31]
	v_lshl_add_u64 v[174:175], v[174:175], 0, s[30:31]
	s_cmp_eq_u32 s42, s41
	v_lshl_add_u64 v[176:177], v[176:177], 0, s[34:35]
	s_waitcnt vmcnt(0) lgkmcnt(0)
	s_barrier
	s_cbranch_scc1 .LBB0_292
